# in-proj epilogue: the 8 serialized per-block bias loads (load+vmcnt0 each) reduced to 2 loads issued together, values kept in v140/v141
# speedup vs baseline: 1.0079x; 1.0026x over previous
; DEV unsigned short f2bf(float f) { return (unsigned short)(pack2(f, 0.f) & 0xFFFFu); }
; template <int EPI>
; __device__ void gemm_phase256(const Params& P, int l, const bf16_t* __restrict__ A, const bf16_t* __restrict__ Bt, int NT, char* smem) {
;     ...
; #pragma unroll
;       for (int mi = 0; mi < 4; ++mi)
; #pragma unroll
;         for (int ni = 0; ni < 2; ++ni) {
;           const int col = wn * 64 + ni * 32 + lr;
;           const int n = n0 + col;
;           const float bias = (EPI == 0) ? ((n < NIN) ? P.b_in[l * NIN + n] : 0.f) : 0.f;
;           const int rb = wm * 128 + mi * 32 + 4 * hk;
; #pragma unroll
;           for (int i = 0; i < 16; ++i) Cs[(rb + (i & 3) + 8 * (i >> 2)) * 136 + col] = f2bf(acc[mi][ni][i] + bias);
;         }
.LBB0_249:
	s_or_b64 exec, exec, s[38:39]
	v_or_b32_e32 v141, s0, v227
	v_cmp_gt_i32_e64 s[40:41], s1, v141
	s_nop 0
	s_and_saveexec_b64 s[38:39], s[40:41]
	s_cbranch_execz .Lipb_bias1_done
	s_ashr_i32 s1, s0, 31
	v_lshl_add_u64 v[130:131], s[0:1], 0, v[194:195]
	v_lshl_add_u64 v[130:131], v[130:131], 2, s[44:45]
	global_load_dword v130, v[130:131], off offset:128
.Lipb_bias1_done:
	s_or_b64 exec, exec, s[38:39]
	s_waitcnt vmcnt(0)
	v_mov_b32_e32 v140, v129
	v_mov_b32_e32 v141, v130
	v_add_f32_e32 v131, v112, v129
	v_cvt_pk_bf16_f32 v131, v131, s0
	ds_write_b16 v228, v131
	v_add_f32_e32 v131, v113, v129
	v_cvt_pk_bf16_f32 v131, v131, s0
	ds_write_b16 v228, v131 offset:272
	v_add_f32_e32 v131, v114, v129
	v_cvt_pk_bf16_f32 v131, v131, s0
	ds_write_b16 v228, v131 offset:544
	v_add_f32_e32 v131, v115, v129
	v_cvt_pk_bf16_f32 v131, v131, s0
	ds_write_b16 v228, v131 offset:816
	v_add_f32_e32 v131, v116, v129
	v_cvt_pk_bf16_f32 v131, v131, s0
	ds_write_b16 v228, v131 offset:2176
	v_add_f32_e32 v131, v117, v129
	v_cvt_pk_bf16_f32 v131, v131, s0
	ds_write_b16 v228, v131 offset:2448
	v_add_f32_e32 v131, v118, v129
	v_cvt_pk_bf16_f32 v131, v131, s0
	ds_write_b16 v228, v131 offset:2720
	v_add_f32_e32 v131, v119, v129
	v_cvt_pk_bf16_f32 v131, v131, s0
	ds_write_b16 v228, v131 offset:2992
	v_add_f32_e32 v131, v120, v129
	v_cvt_pk_bf16_f32 v131, v131, s0
	ds_write_b16 v228, v131 offset:4352
	v_add_f32_e32 v131, v121, v129
	v_cvt_pk_bf16_f32 v131, v131, s0
	ds_write_b16 v228, v131 offset:4624
	v_add_f32_e32 v131, v122, v129
	v_cvt_pk_bf16_f32 v131, v131, s0
	ds_write_b16 v228, v131 offset:4896
	v_add_f32_e32 v131, v123, v129
	v_cvt_pk_bf16_f32 v131, v131, s0
	ds_write_b16 v228, v131 offset:5168
	v_add_f32_e32 v131, v124, v129
	v_cvt_pk_bf16_f32 v131, v131, s0
	ds_write_b16 v228, v131 offset:6528
	v_add_f32_e32 v131, v125, v129
	v_cvt_pk_bf16_f32 v131, v131, s0
	ds_write_b16 v228, v131 offset:6800
	v_add_f32_e32 v131, v126, v129
	v_add_f32_e32 v129, v127, v129
	v_cvt_pk_bf16_f32 v129, v129, s0
	ds_write_b16 v228, v129 offset:7344
	v_cvt_pk_bf16_f32 v131, v131, s0
	ds_write_b16 v228, v131 offset:7072
	s_and_saveexec_b64 s[38:39], s[40:41]
	s_cbranch_execz .LBB0_251
	s_ashr_i32 s1, s0, 31
	v_readlane_b32 s44, v251, 10
	v_lshl_add_u64 v[130:131], s[0:1], 0, v[194:195]
	v_readlane_b32 s48, v251, 14
	v_readlane_b32 s49, v251, 15
	v_readlane_b32 s45, v251, 11
	v_readlane_b32 s46, v251, 12
	v_lshl_add_u64 v[130:131], v[130:131], 2, s[48:49]
	v_readlane_b32 s47, v251, 13
	v_readlane_b32 s50, v251, 16
	v_readlane_b32 s51, v251, 17
	v_readlane_b32 s52, v251, 18
	v_readlane_b32 s53, v251, 19
	v_readlane_b32 s54, v251, 20
	v_readlane_b32 s55, v251, 21
	v_readlane_b32 s56, v251, 22
	v_readlane_b32 s57, v251, 23
	v_readlane_b32 s58, v251, 24
	v_readlane_b32 s59, v251, 25
.LBB0_251:
	s_or_b64 exec, exec, s[38:39]
	v_mov_b32_e32 v130, v141
	v_add_f32_e32 v129, v96, v130
	v_cvt_pk_bf16_f32 v129, v129, s0
	ds_write_b16 v228, v129 offset:64
	v_add_f32_e32 v129, v97, v130
	v_cvt_pk_bf16_f32 v129, v129, s0
	ds_write_b16 v228, v129 offset:336
	v_add_f32_e32 v129, v98, v130
	v_cvt_pk_bf16_f32 v129, v129, s0
	ds_write_b16 v228, v129 offset:608
	v_add_f32_e32 v129, v99, v130
	v_cvt_pk_bf16_f32 v129, v129, s0
	ds_write_b16 v228, v129 offset:880
	v_add_f32_e32 v129, v100, v130
	v_cvt_pk_bf16_f32 v129, v129, s0
	ds_write_b16 v228, v129 offset:2240
	v_add_f32_e32 v129, v101, v130
	v_cvt_pk_bf16_f32 v129, v129, s0
	ds_write_b16 v228, v129 offset:2512
	v_add_f32_e32 v129, v102, v130
	v_cvt_pk_bf16_f32 v129, v129, s0
	ds_write_b16 v228, v129 offset:2784
	v_add_f32_e32 v129, v103, v130
	v_cvt_pk_bf16_f32 v129, v129, s0
	ds_write_b16 v228, v129 offset:3056
	v_add_f32_e32 v129, v104, v130
	v_cvt_pk_bf16_f32 v129, v129, s0
	ds_write_b16 v228, v129 offset:4416
	v_add_f32_e32 v129, v105, v130
	v_cvt_pk_bf16_f32 v129, v129, s0
	ds_write_b16 v228, v129 offset:4688
	v_add_f32_e32 v129, v106, v130
	v_cvt_pk_bf16_f32 v129, v129, s0
	ds_write_b16 v228, v129 offset:4960
	v_add_f32_e32 v129, v107, v130
	v_cvt_pk_bf16_f32 v129, v129, s0
	ds_write_b16 v228, v129 offset:5232
	v_add_f32_e32 v129, v108, v130
	v_cvt_pk_bf16_f32 v129, v129, s0
	ds_write_b16 v228, v129 offset:6592
	v_add_f32_e32 v129, v109, v130
	v_cvt_pk_bf16_f32 v129, v129, s0
	ds_write_b16 v228, v129 offset:6864
	v_add_f32_e32 v129, v110, v130
	v_cvt_pk_bf16_f32 v129, v129, s0
	ds_write_b16 v228, v129 offset:7136
	v_add_f32_e32 v129, v111, v130
	v_cvt_pk_bf16_f32 v129, v129, s0
	ds_write_b16 v228, v129 offset:7408
	v_mov_b32_e32 v130, 0
	v_mov_b32_e32 v129, 0
	s_and_saveexec_b64 s[38:39], vcc
	s_cbranch_execz .LBB0_253
	v_readlane_b32 s44, v251, 10
	v_ashrrev_i32_e32 v129, 31, v128
	v_readlane_b32 s48, v251, 14
	v_readlane_b32 s49, v251, 15
	v_readlane_b32 s45, v251, 11
	v_readlane_b32 s46, v251, 12
	v_lshl_add_u64 v[132:133], v[128:129], 2, s[48:49]
	v_readlane_b32 s47, v251, 13
	v_readlane_b32 s50, v251, 16
	v_readlane_b32 s51, v251, 17
	v_readlane_b32 s52, v251, 18
	v_readlane_b32 s53, v251, 19
	v_readlane_b32 s54, v251, 20
	v_readlane_b32 s55, v251, 21
	v_readlane_b32 s56, v251, 22
	v_readlane_b32 s57, v251, 23
	v_readlane_b32 s58, v251, 24
	v_readlane_b32 s59, v251, 25
; DEV unsigned short f2bf(float f) { return (unsigned short)(pack2(f, 0.f) & 0xFFFFu); }
; template <int EPI>
; __device__ void gemm_phase256(const Params& P, int l, const bf16_t* __restrict__ A, const bf16_t* __restrict__ Bt, int NT, char* smem) {
;     ...
; #pragma unroll
;       for (int mi = 0; mi < 4; ++mi)
; #pragma unroll
;         for (int ni = 0; ni < 2; ++ni) {
;           const int col = wn * 64 + ni * 32 + lr;
;           const int n = n0 + col;
;           const float bias = (EPI == 0) ? ((n < NIN) ? P.b_in[l * NIN + n] : 0.f) : 0.f;
;           const int rb = wm * 128 + mi * 32 + 4 * hk;
; #pragma unroll
;           for (int i = 0; i < 16; ++i) Cs[(rb + (i & 3) + 8 * (i >> 2)) * 136 + col] = f2bf(acc[mi][ni][i] + bias);
;         }
.LBB0_253:
	s_or_b64 exec, exec, s[38:39]
	v_mov_b32_e32 v129, v140
	v_add_f32_e32 v131, v80, v129
	v_cvt_pk_bf16_f32 v131, v131, s0
	ds_write_b16 v228, v131 offset:8704
	v_add_f32_e32 v131, v81, v129
	v_cvt_pk_bf16_f32 v131, v131, s0
	ds_write_b16 v228, v131 offset:8976
	v_add_f32_e32 v131, v82, v129
	v_cvt_pk_bf16_f32 v131, v131, s0
	ds_write_b16 v228, v131 offset:9248
	v_add_f32_e32 v131, v83, v129
	v_cvt_pk_bf16_f32 v131, v131, s0
	ds_write_b16 v228, v131 offset:9520
	v_add_f32_e32 v131, v84, v129
	v_cvt_pk_bf16_f32 v131, v131, s0
	ds_write_b16 v228, v131 offset:10880
	v_add_f32_e32 v131, v85, v129
	v_cvt_pk_bf16_f32 v131, v131, s0
	ds_write_b16 v228, v131 offset:11152
	v_add_f32_e32 v131, v86, v129
	v_cvt_pk_bf16_f32 v131, v131, s0
	ds_write_b16 v228, v131 offset:11424
	v_add_f32_e32 v131, v87, v129
	v_cvt_pk_bf16_f32 v131, v131, s0
	ds_write_b16 v228, v131 offset:11696
	v_add_f32_e32 v131, v88, v129
	v_cvt_pk_bf16_f32 v131, v131, s0
	ds_write_b16 v228, v131 offset:13056
	v_add_f32_e32 v131, v89, v129
	v_cvt_pk_bf16_f32 v131, v131, s0
	ds_write_b16 v228, v131 offset:13328
	v_add_f32_e32 v131, v90, v129
	v_cvt_pk_bf16_f32 v131, v131, s0
	ds_write_b16 v228, v131 offset:13600
	v_add_f32_e32 v131, v91, v129
	v_cvt_pk_bf16_f32 v131, v131, s0
	ds_write_b16 v228, v131 offset:13872
	v_add_f32_e32 v131, v92, v129
	v_cvt_pk_bf16_f32 v131, v131, s0
	ds_write_b16 v228, v131 offset:15232
	v_add_f32_e32 v131, v93, v129
	v_cvt_pk_bf16_f32 v131, v131, s0
	ds_write_b16 v228, v131 offset:15504
	v_add_f32_e32 v131, v94, v129
	v_add_f32_e32 v129, v95, v129
	v_cvt_pk_bf16_f32 v131, v131, s0
	v_cvt_pk_bf16_f32 v129, v129, s0
	ds_write_b16 v228, v131 offset:15776
	ds_write_b16 v228, v129 offset:16048
	s_and_saveexec_b64 s[38:39], s[40:41]
	s_cbranch_execz .LBB0_255
	s_ashr_i32 s1, s0, 31
	v_readlane_b32 s44, v251, 10
	v_lshl_add_u64 v[130:131], s[0:1], 0, v[194:195]
	v_readlane_b32 s48, v251, 14
	v_readlane_b32 s49, v251, 15
	v_readlane_b32 s45, v251, 11
	v_readlane_b32 s46, v251, 12
	v_lshl_add_u64 v[130:131], v[130:131], 2, s[48:49]
	v_readlane_b32 s47, v251, 13
	v_readlane_b32 s50, v251, 16
	v_readlane_b32 s51, v251, 17
	v_readlane_b32 s52, v251, 18
	v_readlane_b32 s53, v251, 19
	v_readlane_b32 s54, v251, 20
	v_readlane_b32 s55, v251, 21
	v_readlane_b32 s56, v251, 22
	v_readlane_b32 s57, v251, 23
	v_readlane_b32 s58, v251, 24
	v_readlane_b32 s59, v251, 25
.LBB0_255:
	s_or_b64 exec, exec, s[38:39]
	v_mov_b32_e32 v130, v141
	v_add_f32_e32 v129, v64, v130
	v_cvt_pk_bf16_f32 v129, v129, s0
	ds_write_b16 v228, v129 offset:8768
	v_add_f32_e32 v129, v65, v130
	v_cvt_pk_bf16_f32 v129, v129, s0
	ds_write_b16 v228, v129 offset:9040
	v_add_f32_e32 v129, v66, v130
	v_cvt_pk_bf16_f32 v129, v129, s0
	ds_write_b16 v228, v129 offset:9312
	v_add_f32_e32 v129, v67, v130
	v_cvt_pk_bf16_f32 v129, v129, s0
	ds_write_b16 v228, v129 offset:9584
	v_add_f32_e32 v129, v68, v130
	v_cvt_pk_bf16_f32 v129, v129, s0
	ds_write_b16 v228, v129 offset:10944
	v_add_f32_e32 v129, v69, v130
	v_cvt_pk_bf16_f32 v129, v129, s0
	ds_write_b16 v228, v129 offset:11216
	v_add_f32_e32 v129, v70, v130
	v_cvt_pk_bf16_f32 v129, v129, s0
	ds_write_b16 v228, v129 offset:11488
	v_add_f32_e32 v129, v71, v130
	v_cvt_pk_bf16_f32 v129, v129, s0
	ds_write_b16 v228, v129 offset:11760
	v_add_f32_e32 v129, v72, v130
	v_cvt_pk_bf16_f32 v129, v129, s0
	ds_write_b16 v228, v129 offset:13120
	v_add_f32_e32 v129, v73, v130
	v_cvt_pk_bf16_f32 v129, v129, s0
	ds_write_b16 v228, v129 offset:13392
	v_add_f32_e32 v129, v74, v130
	v_cvt_pk_bf16_f32 v129, v129, s0
	ds_write_b16 v228, v129 offset:13664
	v_add_f32_e32 v129, v75, v130
	v_cvt_pk_bf16_f32 v129, v129, s0
	ds_write_b16 v228, v129 offset:13936
	v_add_f32_e32 v129, v76, v130
	v_cvt_pk_bf16_f32 v129, v129, s0
	ds_write_b16 v228, v129 offset:15296
	v_add_f32_e32 v129, v77, v130
	v_cvt_pk_bf16_f32 v129, v129, s0
	ds_write_b16 v228, v129 offset:15568
	v_add_f32_e32 v129, v78, v130
	v_cvt_pk_bf16_f32 v129, v129, s0
	ds_write_b16 v228, v129 offset:15840
	v_add_f32_e32 v129, v79, v130
	v_cvt_pk_bf16_f32 v129, v129, s0
	ds_write_b16 v228, v129 offset:16112
	v_mov_b32_e32 v130, 0
	v_mov_b32_e32 v129, 0
	s_and_saveexec_b64 s[38:39], vcc
	s_cbranch_execz .LBB0_257
	v_readlane_b32 s44, v251, 10
	v_ashrrev_i32_e32 v129, 31, v128
	v_readlane_b32 s48, v251, 14
	v_readlane_b32 s49, v251, 15
	v_readlane_b32 s45, v251, 11
	v_readlane_b32 s46, v251, 12
	v_lshl_add_u64 v[132:133], v[128:129], 2, s[48:49]
	v_readlane_b32 s47, v251, 13
	v_readlane_b32 s50, v251, 16
	v_readlane_b32 s51, v251, 17
	v_readlane_b32 s52, v251, 18
	v_readlane_b32 s53, v251, 19
	v_readlane_b32 s54, v251, 20
	v_readlane_b32 s55, v251, 21
	v_readlane_b32 s56, v251, 22
	v_readlane_b32 s57, v251, 23
	v_readlane_b32 s58, v251, 24
	v_readlane_b32 s59, v251, 25
; DEV unsigned short f2bf(float f) { return (unsigned short)(pack2(f, 0.f) & 0xFFFFu); }
; template <int EPI>
; __device__ void gemm_phase256(const Params& P, int l, const bf16_t* __restrict__ A, const bf16_t* __restrict__ Bt, int NT, char* smem) {
;     ...
; #pragma unroll
;       for (int mi = 0; mi < 4; ++mi)
; #pragma unroll
;         for (int ni = 0; ni < 2; ++ni) {
;           const int col = wn * 64 + ni * 32 + lr;
;           const int n = n0 + col;
;           const float bias = (EPI == 0) ? ((n < NIN) ? P.b_in[l * NIN + n] : 0.f) : 0.f;
;           const int rb = wm * 128 + mi * 32 + 4 * hk;
; #pragma unroll
;           for (int i = 0; i < 16; ++i) Cs[(rb + (i & 3) + 8 * (i >> 2)) * 136 + col] = f2bf(acc[mi][ni][i] + bias);
;         }
.LBB0_257:
	s_or_b64 exec, exec, s[38:39]
	v_mov_b32_e32 v129, v140
	v_add_f32_e32 v131, v48, v129
	v_cvt_pk_bf16_f32 v131, v131, s0
	ds_write_b16 v228, v131 offset:17408
	v_add_f32_e32 v131, v49, v129
	v_cvt_pk_bf16_f32 v131, v131, s0
	ds_write_b16 v228, v131 offset:17680
	v_add_f32_e32 v131, v50, v129
	v_cvt_pk_bf16_f32 v131, v131, s0
	ds_write_b16 v228, v131 offset:17952
	v_add_f32_e32 v131, v51, v129
	v_cvt_pk_bf16_f32 v131, v131, s0
	ds_write_b16 v228, v131 offset:18224
	v_add_f32_e32 v131, v52, v129
	v_cvt_pk_bf16_f32 v131, v131, s0
	ds_write_b16 v228, v131 offset:19584
	v_add_f32_e32 v131, v53, v129
	v_cvt_pk_bf16_f32 v131, v131, s0
	ds_write_b16 v228, v131 offset:19856
	v_add_f32_e32 v131, v54, v129
	v_cvt_pk_bf16_f32 v131, v131, s0
	ds_write_b16 v228, v131 offset:20128
	v_add_f32_e32 v131, v55, v129
	v_cvt_pk_bf16_f32 v131, v131, s0
	ds_write_b16 v228, v131 offset:20400
	v_add_f32_e32 v131, v56, v129
	v_cvt_pk_bf16_f32 v131, v131, s0
	ds_write_b16 v228, v131 offset:21760
	v_add_f32_e32 v131, v57, v129
	v_cvt_pk_bf16_f32 v131, v131, s0
	ds_write_b16 v228, v131 offset:22032
	v_add_f32_e32 v131, v58, v129
	v_cvt_pk_bf16_f32 v131, v131, s0
	ds_write_b16 v228, v131 offset:22304
	v_add_f32_e32 v131, v59, v129
	v_cvt_pk_bf16_f32 v131, v131, s0
	ds_write_b16 v228, v131 offset:22576
	v_add_f32_e32 v131, v60, v129
	v_cvt_pk_bf16_f32 v131, v131, s0
	ds_write_b16 v228, v131 offset:23936
	v_add_f32_e32 v131, v61, v129
	v_cvt_pk_bf16_f32 v131, v131, s0
	ds_write_b16 v228, v131 offset:24208
	v_add_f32_e32 v131, v62, v129
	v_add_f32_e32 v129, v63, v129
	v_cvt_pk_bf16_f32 v131, v131, s0
	v_cvt_pk_bf16_f32 v129, v129, s0
	ds_write_b16 v228, v131 offset:24480
	ds_write_b16 v228, v129 offset:24752
	s_and_saveexec_b64 s[38:39], s[40:41]
	s_cbranch_execz .LBB0_259
	s_ashr_i32 s1, s0, 31
	v_readlane_b32 s44, v251, 10
	v_lshl_add_u64 v[130:131], s[0:1], 0, v[194:195]
	v_readlane_b32 s48, v251, 14
	v_readlane_b32 s49, v251, 15
	v_readlane_b32 s45, v251, 11
	v_readlane_b32 s46, v251, 12
	v_lshl_add_u64 v[130:131], v[130:131], 2, s[48:49]
	v_readlane_b32 s47, v251, 13
	v_readlane_b32 s50, v251, 16
	v_readlane_b32 s51, v251, 17
	v_readlane_b32 s52, v251, 18
	v_readlane_b32 s53, v251, 19
	v_readlane_b32 s54, v251, 20
	v_readlane_b32 s55, v251, 21
	v_readlane_b32 s56, v251, 22
	v_readlane_b32 s57, v251, 23
	v_readlane_b32 s58, v251, 24
	v_readlane_b32 s59, v251, 25
.LBB0_259:
	s_or_b64 exec, exec, s[38:39]
	v_mov_b32_e32 v130, v141
	v_add_f32_e32 v129, v32, v130
	v_cvt_pk_bf16_f32 v129, v129, s0
	ds_write_b16 v228, v129 offset:17472
	v_add_f32_e32 v129, v33, v130
	v_cvt_pk_bf16_f32 v129, v129, s0
	ds_write_b16 v228, v129 offset:17744
	v_add_f32_e32 v129, v34, v130
	v_cvt_pk_bf16_f32 v129, v129, s0
	ds_write_b16 v228, v129 offset:18016
	v_add_f32_e32 v129, v35, v130
	v_cvt_pk_bf16_f32 v129, v129, s0
	ds_write_b16 v228, v129 offset:18288
	v_add_f32_e32 v129, v36, v130
	v_cvt_pk_bf16_f32 v129, v129, s0
	ds_write_b16 v228, v129 offset:19648
	v_add_f32_e32 v129, v37, v130
	v_cvt_pk_bf16_f32 v129, v129, s0
	ds_write_b16 v228, v129 offset:19920
	v_add_f32_e32 v129, v38, v130
	v_cvt_pk_bf16_f32 v129, v129, s0
	ds_write_b16 v228, v129 offset:20192
	v_add_f32_e32 v129, v39, v130
	v_cvt_pk_bf16_f32 v129, v129, s0
	ds_write_b16 v228, v129 offset:20464
	v_add_f32_e32 v129, v40, v130
	v_cvt_pk_bf16_f32 v129, v129, s0
	ds_write_b16 v228, v129 offset:21824
	v_add_f32_e32 v129, v41, v130
	v_cvt_pk_bf16_f32 v129, v129, s0
	ds_write_b16 v228, v129 offset:22096
	v_add_f32_e32 v129, v42, v130
	v_cvt_pk_bf16_f32 v129, v129, s0
	ds_write_b16 v228, v129 offset:22368
	v_add_f32_e32 v129, v43, v130
	v_cvt_pk_bf16_f32 v129, v129, s0
	ds_write_b16 v228, v129 offset:22640
	v_add_f32_e32 v129, v44, v130
	v_cvt_pk_bf16_f32 v129, v129, s0
	ds_write_b16 v228, v129 offset:24000
	v_add_f32_e32 v129, v45, v130
	v_cvt_pk_bf16_f32 v129, v129, s0
	ds_write_b16 v228, v129 offset:24272
	v_add_f32_e32 v129, v46, v130
	v_cvt_pk_bf16_f32 v129, v129, s0
	ds_write_b16 v228, v129 offset:24544
	v_add_f32_e32 v129, v47, v130
	v_cvt_pk_bf16_f32 v129, v129, s0
	ds_write_b16 v228, v129 offset:24816
	v_mov_b32_e32 v130, 0
	v_mov_b32_e32 v129, 0
	s_and_saveexec_b64 s[38:39], vcc
	s_cbranch_execz .LBB0_261
	v_readlane_b32 s44, v251, 10
	v_ashrrev_i32_e32 v129, 31, v128
	v_readlane_b32 s48, v251, 14
	v_readlane_b32 s49, v251, 15
	v_readlane_b32 s45, v251, 11
	v_readlane_b32 s46, v251, 12
	v_lshl_add_u64 v[128:129], v[128:129], 2, s[48:49]
	v_readlane_b32 s47, v251, 13
	v_readlane_b32 s50, v251, 16
	v_readlane_b32 s51, v251, 17
	v_readlane_b32 s52, v251, 18
	v_readlane_b32 s53, v251, 19
	v_readlane_b32 s54, v251, 20
	v_readlane_b32 s55, v251, 21
	v_readlane_b32 s56, v251, 22
	v_readlane_b32 s57, v251, 23
	v_readlane_b32 s58, v251, 24
	v_readlane_b32 s59, v251, 25
; DEV unsigned short f2bf(float f) { return (unsigned short)(pack2(f, 0.f) & 0xFFFFu); }
; template <int EPI>
; __device__ void gemm_phase256(const Params& P, int l, const bf16_t* __restrict__ A, const bf16_t* __restrict__ Bt, int NT, char* smem) {
;     ...
; #pragma unroll
;       for (int mi = 0; mi < 4; ++mi)
; #pragma unroll
;         for (int ni = 0; ni < 2; ++ni) {
;           const int col = wn * 64 + ni * 32 + lr;
;           const int n = n0 + col;
;           const float bias = (EPI == 0) ? ((n < NIN) ? P.b_in[l * NIN + n] : 0.f) : 0.f;
;           const int rb = wm * 128 + mi * 32 + 4 * hk;
; #pragma unroll
;           for (int i = 0; i < 16; ++i) Cs[(rb + (i & 3) + 8 * (i >> 2)) * 136 + col] = f2bf(acc[mi][ni][i] + bias);
;         }
;       __syncthreads();
;       bf16_t* dstb; int dstride, cbase, nvalid;
;       if (EPI == 0) { dstb = P.H; dstride = HS; cbase = n0 - (nt == 16 ? 128 : (nt == 18 ? 256 : 0)); nvalid = (NIN - n0 < 128) ? (NIN - n0) : 128; }
.LBB0_261:
	s_or_b64 exec, exec, s[38:39]
	v_mov_b32_e32 v129, v140
	v_add_f32_e32 v128, v16, v129
	v_cvt_pk_bf16_f32 v128, v128, s0
	ds_write_b16 v228, v128 offset:26112
	v_add_f32_e32 v128, v17, v129
	v_cvt_pk_bf16_f32 v128, v128, s0
	ds_write_b16 v228, v128 offset:26384
	v_add_f32_e32 v128, v18, v129
	v_cvt_pk_bf16_f32 v128, v128, s0
	ds_write_b16 v228, v128 offset:26656
	v_add_f32_e32 v128, v19, v129
	v_cvt_pk_bf16_f32 v128, v128, s0
	ds_write_b16 v228, v128 offset:26928
	v_add_f32_e32 v128, v20, v129
	v_cvt_pk_bf16_f32 v128, v128, s0
	ds_write_b16 v228, v128 offset:28288
	v_add_f32_e32 v128, v21, v129
	v_cvt_pk_bf16_f32 v128, v128, s0
	ds_write_b16 v228, v128 offset:28560
	v_add_f32_e32 v128, v22, v129
	v_cvt_pk_bf16_f32 v128, v128, s0
	ds_write_b16 v228, v128 offset:28832
	v_add_f32_e32 v128, v23, v129
	v_cvt_pk_bf16_f32 v128, v128, s0
	ds_write_b16 v228, v128 offset:29104
	v_add_f32_e32 v128, v24, v129
	v_cvt_pk_bf16_f32 v128, v128, s0
	ds_write_b16 v228, v128 offset:30464
	v_add_f32_e32 v128, v25, v129
	v_cvt_pk_bf16_f32 v128, v128, s0
	ds_write_b16 v228, v128 offset:30736
	v_add_f32_e32 v128, v26, v129
	v_cvt_pk_bf16_f32 v128, v128, s0
	ds_write_b16 v228, v128 offset:31008
	v_add_f32_e32 v128, v27, v129
	v_cvt_pk_bf16_f32 v128, v128, s0
	ds_write_b16 v228, v128 offset:31280
	v_add_f32_e32 v128, v28, v129
	v_cvt_pk_bf16_f32 v128, v128, s0
	ds_write_b16 v228, v128 offset:32640
	v_add_f32_e32 v128, v29, v129
	v_cvt_pk_bf16_f32 v128, v128, s0
	ds_write_b16 v228, v128 offset:32912
	v_add_f32_e32 v128, v30, v129
	v_cvt_pk_bf16_f32 v128, v128, s0
	ds_write_b16 v228, v128 offset:33184
	v_add_f32_e32 v128, v31, v129
	v_cvt_pk_bf16_f32 v128, v128, s0
	ds_write_b16 v228, v128 offset:33456
	s_and_saveexec_b64 s[38:39], s[40:41]
	s_cbranch_execz .LBB0_263
	s_ashr_i32 s1, s0, 31
	v_readlane_b32 s40, v251, 10
	v_lshl_add_u64 v[128:129], s[0:1], 0, v[194:195]
	v_readlane_b32 s44, v251, 14
	v_readlane_b32 s45, v251, 15
	v_readlane_b32 s41, v251, 11
	v_readlane_b32 s42, v251, 12
	v_lshl_add_u64 v[128:129], v[128:129], 2, s[44:45]
	v_readlane_b32 s43, v251, 13
	v_readlane_b32 s46, v251, 16
	v_readlane_b32 s47, v251, 17
	v_readlane_b32 s48, v251, 18
	v_readlane_b32 s49, v251, 19
	v_readlane_b32 s50, v251, 20
	v_readlane_b32 s51, v251, 21
	v_readlane_b32 s52, v251, 22
	v_readlane_b32 s53, v251, 23
	v_readlane_b32 s54, v251, 24
	v_readlane_b32 s55, v251, 25
.LBB0_263:
	s_or_b64 exec, exec, s[38:39]
	v_mov_b32_e32 v130, v141
	v_add_f32_e32 v128, v0, v130
	v_cvt_pk_bf16_f32 v128, v128, s0
	ds_write_b16 v228, v128 offset:26176
	v_add_f32_e32 v128, v1, v130
	v_cvt_pk_bf16_f32 v128, v128, s0
	ds_write_b16 v228, v128 offset:26448
	v_add_f32_e32 v128, v2, v130
	v_cvt_pk_bf16_f32 v128, v128, s0
	ds_write_b16 v228, v128 offset:26720
	v_add_f32_e32 v128, v3, v130
	v_cvt_pk_bf16_f32 v128, v128, s0
	ds_write_b16 v228, v128 offset:26992
	v_add_f32_e32 v128, v4, v130
	v_cvt_pk_bf16_f32 v128, v128, s0
	ds_write_b16 v228, v128 offset:28352
	v_add_f32_e32 v128, v5, v130
	v_cvt_pk_bf16_f32 v128, v128, s0
	ds_write_b16 v228, v128 offset:28624
	v_add_f32_e32 v128, v6, v130
	v_cvt_pk_bf16_f32 v128, v128, s0
	ds_write_b16 v228, v128 offset:28896
	v_add_f32_e32 v128, v7, v130
	v_cvt_pk_bf16_f32 v128, v128, s0
	ds_write_b16 v228, v128 offset:29168
	v_add_f32_e32 v128, v8, v130
	v_cvt_pk_bf16_f32 v128, v128, s0
	ds_write_b16 v228, v128 offset:30528
	v_add_f32_e32 v128, v9, v130
	v_cvt_pk_bf16_f32 v128, v128, s0
	ds_write_b16 v228, v128 offset:30800
	v_add_f32_e32 v128, v10, v130
	v_cvt_pk_bf16_f32 v128, v128, s0
	ds_write_b16 v228, v128 offset:31072
	v_add_f32_e32 v128, v11, v130
	v_cvt_pk_bf16_f32 v128, v128, s0
	ds_write_b16 v228, v128 offset:31344
	v_add_f32_e32 v128, v12, v130
	v_cvt_pk_bf16_f32 v128, v128, s0
	ds_write_b16 v228, v128 offset:32704
	v_add_f32_e32 v128, v13, v130
	v_cvt_pk_bf16_f32 v128, v128, s0
	s_cmp_eq_u32 s33, 18
	ds_write_b16 v228, v128 offset:32976
	v_add_f32_e32 v128, v14, v130
	s_cselect_b32 s37, 0xffffff00, 0
	s_cmp_lg_u32 s33, 16
	v_cvt_pk_bf16_f32 v128, v128, s0
	s_cselect_b32 s37, s37, 0xffffff80
	ds_write_b16 v228, v128 offset:33248
	v_add_f32_e32 v128, v15, v130
	s_add_i32 s38, s37, s0
	v_cvt_pk_bf16_f32 v128, v128, s0
	s_ashr_i32 s39, s38, 31
	ds_write_b16 v228, v128 offset:33520
	s_mov_b32 s1, 0
	v_cmp_lt_i32_e32 vcc, s0, v185
	v_lshl_add_u64 v[128:129], s[38:39], 1, v[192:193]
	s_waitcnt lgkmcnt(0)
	s_barrier
	s_branch .LBB0_265
